# sgu prompt path hand-written with cross-unit prefetch of SSV VT U loads and relaxed vmcnt
# baseline (speedup 1.0000x reference)
.LBB0_1405:
	s_cmp_lt_i32 s40, 14
	s_cselect_b64 s[8:9], -1, 0
	s_waitcnt lgkmcnt(0)
	s_and_b64 s[14:15], s[8:9], s[6:7]
	s_andn2_b64 vcc, exec, s[14:15]
	s_cbranch_vccnz .LBB0_1528
	s_mov_b32 s101, s2
	s_cmpk_lt_u32 s101, 0x800
	s_cbranch_scc0 .Lmy_sgu_done
	s_and_b32 s3, s2, 7
	v_readfirstlane_b32 s6, v226
	s_load_dwordx2 s[24:25], s[0:1], 0xc0
	s_load_dwordx2 s[26:27], s[0:1], 0xc8
	s_load_dwordx2 s[28:29], s[0:1], 0xd0
	s_lshr_b32 s6, s6, 6
	s_lshr_b32 s7, s6, 2
	s_and_b32 s6, s6, 3
	v_and_b32_e32 v1, 63, v226
	v_and_b32_e32 v2, 31, v1
	v_lshrrev_b32_e32 v3, 5, v1
	v_and_b32_e32 v4, 0x7f, v226
	v_lshlrev_b32_e32 v4, 2, v4
	s_lshl_b32 s8, s3, 7
	s_lshl_b32 s9, s7, 6
	s_add_i32 s8, s8, s9
	v_add_u32_e32 v5, s8, v2
	v_lshlrev_b32_e32 v14, 2, v5
	s_waitcnt lgkmcnt(0)
	global_load_dword v15, v14, s[24:25] offset:128
	global_load_dword v14, v14, s[24:25]
	s_lshl_b32 s9, s6, 5
	s_lshl_b32 s10, s3, 7
	s_add_i32 s10, s10, s9
	v_lshl_add_u32 v16, v3, 2, s10
	v_lshlrev_b32_e32 v16, 2, v16
	global_load_dword v31, v16, s[28:29] offset:108
	global_load_dword v30, v16, s[28:29] offset:104
	global_load_dword v29, v16, s[28:29] offset:100
	global_load_dword v28, v16, s[28:29] offset:96
	global_load_dword v27, v16, s[28:29] offset:76
	global_load_dword v26, v16, s[28:29] offset:72
	global_load_dword v25, v16, s[28:29] offset:68
	global_load_dword v24, v16, s[28:29] offset:64
	global_load_dword v23, v16, s[28:29] offset:44
	global_load_dword v22, v16, s[28:29] offset:40
	global_load_dword v21, v16, s[28:29] offset:36
	global_load_dword v20, v16, s[28:29] offset:32
	global_load_dword v19, v16, s[28:29] offset:12
	global_load_dword v18, v16, s[28:29] offset:8
	global_load_dword v17, v16, s[28:29] offset:4
	global_load_dword v16, v16, s[28:29]
	s_lshl_b32 s11, s3, 16
	s_lshl_b32 s12, s6, 14
	s_add_i32 s11, s11, s12
	v_lshlrev_b32_e32 v32, 9, v2
	v_lshl_add_u32 v32, v3, 5, v32
	v_add_u32_e32 v32, s11, v32
	global_load_dwordx4 v[92:95], v32, s[26:27] offset:464
	global_load_dwordx4 v[88:91], v32, s[26:27] offset:448
	global_load_dwordx4 v[84:87], v32, s[26:27] offset:400
	global_load_dwordx4 v[80:83], v32, s[26:27] offset:384
	global_load_dwordx4 v[76:79], v32, s[26:27] offset:336
	global_load_dwordx4 v[72:75], v32, s[26:27] offset:320
	global_load_dwordx4 v[68:71], v32, s[26:27] offset:272
	global_load_dwordx4 v[64:67], v32, s[26:27] offset:256
	global_load_dwordx4 v[60:63], v32, s[26:27] offset:208
	global_load_dwordx4 v[56:59], v32, s[26:27] offset:192
	global_load_dwordx4 v[52:55], v32, s[26:27] offset:144
	global_load_dwordx4 v[48:51], v32, s[26:27] offset:128
	global_load_dwordx4 v[44:47], v32, s[26:27] offset:80
	global_load_dwordx4 v[40:43], v32, s[26:27] offset:64
	global_load_dwordx4 v[36:39], v32, s[26:27] offset:16
	global_load_dwordx4 v[32:35], v32, s[26:27]
	v_mov_b32_e32 v6, 0x10600
	v_mul_u32_u24_e32 v5, v5, v6
	v_lshl_add_u32 v5, v3, 4, v5
	v_add_u32_e32 v6, 0x20c000, v5
	v_lshlrev_b32_e32 v7, 5, v3
	s_mul_i32 s12, s6, 0x4200
	s_lshl_b32 s13, s7, 8
	s_add_i32 s12, s12, s13
	s_addk_i32 s12, 0x400
	v_mul_u32_u24_e32 v8, 0x840, v3
	v_lshl_add_u32 v8, v2, 2, v8
	v_add_u32_e32 v8, s12, v8
	v_lshrrev_b32_e32 v9, 4, v226
	v_mul_u32_u24_e32 v9, 0x210, v9
	v_and_b32_e32 v10, 15, v226
	v_lshl_add_u32 v9, v10, 5, v9
	v_add_u32_e32 v9, 0x400, v9
	v_lshrrev_b32_e32 v11, 4, v226
	v_lshlrev_b32_e32 v11, 11, v11
	v_lshl_add_u32 v10, v10, 4, v11
	v_add_u32_e32 v11, 0x10000, v10
	v_add_u32_e32 v12, 0x20000, v10
	v_add_u32_e32 v13, 0x30000, v10
	s_waitcnt vmcnt(30)
	s_mov_b32 s50, s101
	s_lshr_b32 s16, s50, 3
	s_lshl_b32 s16, s16, 7
	s_lshl_b32 s17, s16, 2
	s_add_u32 s22, s38, s17
	s_addc_u32 s23, s39, 0
	s_add_u32 s22, s22, 0x3000000
	s_addc_u32 s23, s23, 0
	s_lshl_b32 s17, s16, 1
	s_add_u32 s18, s38, s17
	s_addc_u32 s19, s39, 0
	s_add_u32 s18, s18, 0xc500000
	s_addc_u32 s19, s19, 0
	s_lshl_b32 s17, s16, 11
	s_lshl_b32 s20, s3, 8
	s_add_i32 s17, s17, s20
	s_add_u32 s20, s38, s17
	s_addc_u32 s21, s39, 0
	s_add_u32 s46, s20, 0x10700000
	s_addc_u32 s47, s21, 0
	s_add_u32 s20, s20, 0x8400000
	s_addc_u32 s21, s21, 0
	global_load_dword v204, v4, s[22:23]
	s_add_u32 s22, s22, 0x20c00
	s_addc_u32 s23, s23, 0
	global_load_dword v205, v4, s[22:23]
	s_add_u32 s22, s22, 0x20c00
	s_addc_u32 s23, s23, 0
	global_load_dword v206, v4, s[22:23]
	s_add_u32 s22, s22, 0x20c00
	s_addc_u32 s23, s23, 0
	global_load_dword v207, v4, s[22:23]
	s_add_u32 s22, s22, 0x20c00
	s_addc_u32 s23, s23, 0
	global_load_dword v208, v4, s[22:23]
	s_add_u32 s22, s22, 0x20c00
	s_addc_u32 s23, s23, 0
	global_load_dword v209, v4, s[22:23]
	s_add_u32 s22, s22, 0x20c00
	s_addc_u32 s23, s23, 0
	global_load_dword v210, v4, s[22:23]
	s_add_u32 s22, s22, 0x20c00
	s_addc_u32 s23, s23, 0
	global_load_dword v211, v4, s[22:23]
	global_load_dwordx4 v[96:99], v5, s[18:19]
	global_load_dwordx4 v[128:131], v6, s[18:19]
	global_load_dwordx4 v[100:103], v5, s[18:19] offset:32
	global_load_dwordx4 v[132:135], v6, s[18:19] offset:32
	global_load_dwordx4 v[104:107], v5, s[18:19] offset:64
	global_load_dwordx4 v[136:139], v6, s[18:19] offset:64
	global_load_dwordx4 v[108:111], v5, s[18:19] offset:96
	global_load_dwordx4 v[140:143], v6, s[18:19] offset:96
	global_load_dwordx4 v[112:115], v5, s[18:19] offset:128
	global_load_dwordx4 v[144:147], v6, s[18:19] offset:128
	global_load_dwordx4 v[116:119], v5, s[18:19] offset:160
	global_load_dwordx4 v[148:151], v6, s[18:19] offset:160
	global_load_dwordx4 v[120:123], v5, s[18:19] offset:192
	global_load_dwordx4 v[152:155], v6, s[18:19] offset:192
	global_load_dwordx4 v[124:127], v5, s[18:19] offset:224
	global_load_dwordx4 v[156:159], v6, s[18:19] offset:224
	global_load_dwordx4 v[228:231], v10, s[20:21]
	global_load_dwordx4 v[232:235], v11, s[20:21]
	global_load_dwordx4 v[236:239], v12, s[20:21]
	global_load_dwordx4 v[240:243], v13, s[20:21]
	s_mov_b32 s44, s46
	s_mov_b32 s45, s47
	s_waitcnt vmcnt(4)
.Lmy_sgu_unit:
	s_add_i32 s51, s101, s42
	s_cmpk_lt_u32 s51, 0x800
	s_cselect_b32 s52, 1, 0
	s_cbranch_scc0 .Lmy_sgu_nonext0
	s_mov_b32 s50, s51
	s_lshr_b32 s16, s50, 3
	s_lshl_b32 s16, s16, 7
	s_lshl_b32 s17, s16, 2
	s_add_u32 s22, s38, s17
	s_addc_u32 s23, s39, 0
	s_add_u32 s22, s22, 0x3000000
	s_addc_u32 s23, s23, 0
	s_lshl_b32 s17, s16, 1
	s_add_u32 s18, s38, s17
	s_addc_u32 s19, s39, 0
	s_add_u32 s18, s18, 0xc500000
	s_addc_u32 s19, s19, 0
	s_lshl_b32 s17, s16, 11
	s_lshl_b32 s20, s3, 8
	s_add_i32 s17, s17, s20
	s_add_u32 s20, s38, s17
	s_addc_u32 s21, s39, 0
	s_add_u32 s46, s20, 0x10700000
	s_addc_u32 s47, s21, 0
	s_add_u32 s20, s20, 0x8400000
	s_addc_u32 s21, s21, 0
.Lmy_sgu_nonext0:
	s_waitcnt vmcnt(24)
	v_add_f32_e32 v204, v204, v205
	v_add_f32_e32 v206, v206, v207
	v_add_f32_e32 v208, v208, v209
	v_add_f32_e32 v210, v210, v211
	v_add_f32_e32 v204, v204, v206
	v_add_f32_e32 v208, v208, v210
	v_add_f32_e32 v204, v204, v208
	v_mov_b32_e32 v205, 0x358637bd
	v_fmac_f32_e32 v205, 0x3a800000, v204
	v_rsq_f32_e32 v205, v205
	v_cmp_gt_u32_e32 vcc, 0x80, v226
	s_and_saveexec_b64 s[8:9], vcc
	ds_write_b32 v4, v205
	s_or_b64 exec, exec, s[8:9]
	s_cmp_eq_u32 s52, 0
	s_cbranch_scc1 .Lmy_sgu_nonext1
	global_load_dword v204, v4, s[22:23]
	s_add_u32 s22, s22, 0x20c00
	s_addc_u32 s23, s23, 0
	global_load_dword v205, v4, s[22:23]
	s_add_u32 s22, s22, 0x20c00
	s_addc_u32 s23, s23, 0
	global_load_dword v206, v4, s[22:23]
	s_add_u32 s22, s22, 0x20c00
	s_addc_u32 s23, s23, 0
	global_load_dword v207, v4, s[22:23]
	s_add_u32 s22, s22, 0x20c00
	s_addc_u32 s23, s23, 0
	global_load_dword v208, v4, s[22:23]
	s_add_u32 s22, s22, 0x20c00
	s_addc_u32 s23, s23, 0
	global_load_dword v209, v4, s[22:23]
	s_add_u32 s22, s22, 0x20c00
	s_addc_u32 s23, s23, 0
	global_load_dword v210, v4, s[22:23]
	s_add_u32 s22, s22, 0x20c00
	s_addc_u32 s23, s23, 0
	global_load_dword v211, v4, s[22:23]
.Lmy_sgu_nonext1:
	s_waitcnt lgkmcnt(0)
	s_barrier
	s_cmp_eq_u32 s52, 0
	s_cbranch_scc1 .Lmy_sgu_w8
	s_waitcnt vmcnt(16)
	s_branch .Lmy_sgu_wgo
.Lmy_sgu_w8:
	s_waitcnt vmcnt(8)
.Lmy_sgu_wgo:
	ds_read_b128 v[196:199], v7
	ds_read_b128 v[200:203], v7 offset:16
	s_waitcnt lgkmcnt(0)
	v_mul_f32_e32 v244, v32, v196
	v_mul_f32_e32 v245, v33, v197
	v_mul_f32_e32 v246, v34, v198
	v_mul_f32_e32 v247, v35, v199
	v_mul_f32_e32 v248, v36, v200
	v_mul_f32_e32 v249, v37, v201
	v_mul_f32_e32 v250, v38, v202
	v_mul_f32_e32 v251, v39, v203
	v_cvt_pk_bf16_f32 v192, v244, v245
	v_cvt_pk_bf16_f32 v193, v246, v247
	v_cvt_pk_bf16_f32 v194, v248, v249
	v_cvt_pk_bf16_f32 v195, v250, v251
	s_nop 1
	v_mfma_f32_32x32x16_bf16 v[160:175], v[192:195], v[96:99], 0
	v_mfma_f32_32x32x16_bf16 v[176:191], v[192:195], v[128:131], 0
	ds_read_b128 v[196:199], v7 offset:64
	ds_read_b128 v[200:203], v7 offset:80
	s_waitcnt lgkmcnt(0)
	v_mul_f32_e32 v244, v40, v196
	v_mul_f32_e32 v245, v41, v197
	v_mul_f32_e32 v246, v42, v198
	v_mul_f32_e32 v247, v43, v199
	v_mul_f32_e32 v248, v44, v200
	v_mul_f32_e32 v249, v45, v201
	v_mul_f32_e32 v250, v46, v202
	v_mul_f32_e32 v251, v47, v203
	v_cvt_pk_bf16_f32 v192, v244, v245
	v_cvt_pk_bf16_f32 v193, v246, v247
	v_cvt_pk_bf16_f32 v194, v248, v249
	v_cvt_pk_bf16_f32 v195, v250, v251
	s_nop 1
	v_mfma_f32_32x32x16_bf16 v[160:175], v[192:195], v[100:103], v[160:175]
	v_mfma_f32_32x32x16_bf16 v[176:191], v[192:195], v[132:135], v[176:191]
	ds_read_b128 v[196:199], v7 offset:128
	ds_read_b128 v[200:203], v7 offset:144
	s_waitcnt lgkmcnt(0)
	v_mul_f32_e32 v244, v48, v196
	v_mul_f32_e32 v245, v49, v197
	v_mul_f32_e32 v246, v50, v198
	v_mul_f32_e32 v247, v51, v199
	v_mul_f32_e32 v248, v52, v200
	v_mul_f32_e32 v249, v53, v201
	v_mul_f32_e32 v250, v54, v202
	v_mul_f32_e32 v251, v55, v203
	v_cvt_pk_bf16_f32 v192, v244, v245
	v_cvt_pk_bf16_f32 v193, v246, v247
	v_cvt_pk_bf16_f32 v194, v248, v249
	v_cvt_pk_bf16_f32 v195, v250, v251
	s_nop 1
	v_mfma_f32_32x32x16_bf16 v[160:175], v[192:195], v[104:107], v[160:175]
	v_mfma_f32_32x32x16_bf16 v[176:191], v[192:195], v[136:139], v[176:191]
	ds_read_b128 v[196:199], v7 offset:192
	ds_read_b128 v[200:203], v7 offset:208
	s_waitcnt lgkmcnt(0)
	v_mul_f32_e32 v244, v56, v196
	v_mul_f32_e32 v245, v57, v197
	v_mul_f32_e32 v246, v58, v198
	v_mul_f32_e32 v247, v59, v199
	v_mul_f32_e32 v248, v60, v200
	v_mul_f32_e32 v249, v61, v201
	v_mul_f32_e32 v250, v62, v202
	v_mul_f32_e32 v251, v63, v203
	v_cvt_pk_bf16_f32 v192, v244, v245
	v_cvt_pk_bf16_f32 v193, v246, v247
	v_cvt_pk_bf16_f32 v194, v248, v249
	v_cvt_pk_bf16_f32 v195, v250, v251
	s_nop 1
	v_mfma_f32_32x32x16_bf16 v[160:175], v[192:195], v[108:111], v[160:175]
	v_mfma_f32_32x32x16_bf16 v[176:191], v[192:195], v[140:143], v[176:191]
	s_cmp_lt_u32 s6, 2
	s_cbranch_scc1 .Lmy_sgu_mfma_done
	ds_read_b128 v[196:199], v7 offset:256
	ds_read_b128 v[200:203], v7 offset:272
	s_waitcnt lgkmcnt(0)
	v_mul_f32_e32 v244, v64, v196
	v_mul_f32_e32 v245, v65, v197
	v_mul_f32_e32 v246, v66, v198
	v_mul_f32_e32 v247, v67, v199
	v_mul_f32_e32 v248, v68, v200
	v_mul_f32_e32 v249, v69, v201
	v_mul_f32_e32 v250, v70, v202
	v_mul_f32_e32 v251, v71, v203
	v_cvt_pk_bf16_f32 v192, v244, v245
	v_cvt_pk_bf16_f32 v193, v246, v247
	v_cvt_pk_bf16_f32 v194, v248, v249
	v_cvt_pk_bf16_f32 v195, v250, v251
	s_nop 1
	v_mfma_f32_32x32x16_bf16 v[160:175], v[192:195], v[112:115], v[160:175]
	v_mfma_f32_32x32x16_bf16 v[176:191], v[192:195], v[144:147], v[176:191]
	ds_read_b128 v[196:199], v7 offset:320
	ds_read_b128 v[200:203], v7 offset:336
	s_waitcnt lgkmcnt(0)
	v_mul_f32_e32 v244, v72, v196
	v_mul_f32_e32 v245, v73, v197
	v_mul_f32_e32 v246, v74, v198
	v_mul_f32_e32 v247, v75, v199
	v_mul_f32_e32 v248, v76, v200
	v_mul_f32_e32 v249, v77, v201
	v_mul_f32_e32 v250, v78, v202
	v_mul_f32_e32 v251, v79, v203
	v_cvt_pk_bf16_f32 v192, v244, v245
	v_cvt_pk_bf16_f32 v193, v246, v247
	v_cvt_pk_bf16_f32 v194, v248, v249
	v_cvt_pk_bf16_f32 v195, v250, v251
	s_nop 1
	v_mfma_f32_32x32x16_bf16 v[160:175], v[192:195], v[116:119], v[160:175]
	v_mfma_f32_32x32x16_bf16 v[176:191], v[192:195], v[148:151], v[176:191]
	ds_read_b128 v[196:199], v7 offset:384
	ds_read_b128 v[200:203], v7 offset:400
	s_waitcnt lgkmcnt(0)
	v_mul_f32_e32 v244, v80, v196
	v_mul_f32_e32 v245, v81, v197
	v_mul_f32_e32 v246, v82, v198
	v_mul_f32_e32 v247, v83, v199
	v_mul_f32_e32 v248, v84, v200
	v_mul_f32_e32 v249, v85, v201
	v_mul_f32_e32 v250, v86, v202
	v_mul_f32_e32 v251, v87, v203
	v_cvt_pk_bf16_f32 v192, v244, v245
	v_cvt_pk_bf16_f32 v193, v246, v247
	v_cvt_pk_bf16_f32 v194, v248, v249
	v_cvt_pk_bf16_f32 v195, v250, v251
	s_nop 1
	v_mfma_f32_32x32x16_bf16 v[160:175], v[192:195], v[120:123], v[160:175]
	v_mfma_f32_32x32x16_bf16 v[176:191], v[192:195], v[152:155], v[176:191]
	ds_read_b128 v[196:199], v7 offset:448
	ds_read_b128 v[200:203], v7 offset:464
	s_waitcnt lgkmcnt(0)
	v_mul_f32_e32 v244, v88, v196
	v_mul_f32_e32 v245, v89, v197
	v_mul_f32_e32 v246, v90, v198
	v_mul_f32_e32 v247, v91, v199
	v_mul_f32_e32 v248, v92, v200
	v_mul_f32_e32 v249, v93, v201
	v_mul_f32_e32 v250, v94, v202
	v_mul_f32_e32 v251, v95, v203
	v_cvt_pk_bf16_f32 v192, v244, v245
	v_cvt_pk_bf16_f32 v193, v246, v247
	v_cvt_pk_bf16_f32 v194, v248, v249
	v_cvt_pk_bf16_f32 v195, v250, v251
	s_nop 1
	v_mfma_f32_32x32x16_bf16 v[160:175], v[192:195], v[124:127], v[160:175]
	v_mfma_f32_32x32x16_bf16 v[176:191], v[192:195], v[156:159], v[176:191]
.Lmy_sgu_mfma_done:
	s_cmp_eq_u32 s52, 0
	s_cbranch_scc1 .Lmy_sgu_nonext2
	global_load_dwordx4 v[96:99], v5, s[18:19]
	global_load_dwordx4 v[128:131], v6, s[18:19]
	global_load_dwordx4 v[100:103], v5, s[18:19] offset:32
	global_load_dwordx4 v[132:135], v6, s[18:19] offset:32
	global_load_dwordx4 v[104:107], v5, s[18:19] offset:64
	global_load_dwordx4 v[136:139], v6, s[18:19] offset:64
	global_load_dwordx4 v[108:111], v5, s[18:19] offset:96
	global_load_dwordx4 v[140:143], v6, s[18:19] offset:96
	global_load_dwordx4 v[112:115], v5, s[18:19] offset:128
	global_load_dwordx4 v[144:147], v6, s[18:19] offset:128
	global_load_dwordx4 v[116:119], v5, s[18:19] offset:160
	global_load_dwordx4 v[148:151], v6, s[18:19] offset:160
	global_load_dwordx4 v[120:123], v5, s[18:19] offset:192
	global_load_dwordx4 v[152:155], v6, s[18:19] offset:192
	global_load_dwordx4 v[124:127], v5, s[18:19] offset:224
	global_load_dwordx4 v[156:159], v6, s[18:19] offset:224
.Lmy_sgu_nonext2:
	s_nop 7
	s_nop 7
	v_fma_f32 v160, v160, v14, v16
	v_fma_f32 v176, v176, v15, v16
	v_fma_f32 v161, v161, v14, v17
	v_fma_f32 v177, v177, v15, v17
	v_fma_f32 v162, v162, v14, v18
	v_fma_f32 v178, v178, v15, v18
	v_fma_f32 v163, v163, v14, v19
	v_fma_f32 v179, v179, v15, v19
	v_fma_f32 v164, v164, v14, v20
	v_fma_f32 v180, v180, v15, v20
	v_fma_f32 v165, v165, v14, v21
	v_fma_f32 v181, v181, v15, v21
	v_fma_f32 v166, v166, v14, v22
	v_fma_f32 v182, v182, v15, v22
	v_fma_f32 v167, v167, v14, v23
	v_fma_f32 v183, v183, v15, v23
	v_fma_f32 v168, v168, v14, v24
	v_fma_f32 v184, v184, v15, v24
	v_fma_f32 v169, v169, v14, v25
	v_fma_f32 v185, v185, v15, v25
	v_fma_f32 v170, v170, v14, v26
	v_fma_f32 v186, v186, v15, v26
	v_fma_f32 v171, v171, v14, v27
	v_fma_f32 v187, v187, v15, v27
	v_fma_f32 v172, v172, v14, v28
	v_fma_f32 v188, v188, v15, v28
	v_fma_f32 v173, v173, v14, v29
	v_fma_f32 v189, v189, v15, v29
	v_fma_f32 v174, v174, v14, v30
	v_fma_f32 v190, v190, v15, v30
	v_fma_f32 v175, v175, v14, v31
	v_fma_f32 v191, v191, v15, v31
	ds_write_b32 v8, v160
	ds_write_b32 v8, v176 offset:128
	ds_write_b32 v8, v161 offset:528
	ds_write_b32 v8, v177 offset:656
	ds_write_b32 v8, v162 offset:1056
	ds_write_b32 v8, v178 offset:1184
	ds_write_b32 v8, v163 offset:1584
	ds_write_b32 v8, v179 offset:1712
	ds_write_b32 v8, v164 offset:4224
	ds_write_b32 v8, v180 offset:4352
	ds_write_b32 v8, v165 offset:4752
	ds_write_b32 v8, v181 offset:4880
	ds_write_b32 v8, v166 offset:5280
	ds_write_b32 v8, v182 offset:5408
	ds_write_b32 v8, v167 offset:5808
	ds_write_b32 v8, v183 offset:5936
	ds_write_b32 v8, v168 offset:8448
	ds_write_b32 v8, v184 offset:8576
	ds_write_b32 v8, v169 offset:8976
	ds_write_b32 v8, v185 offset:9104
	ds_write_b32 v8, v170 offset:9504
	ds_write_b32 v8, v186 offset:9632
	ds_write_b32 v8, v171 offset:10032
	ds_write_b32 v8, v187 offset:10160
	ds_write_b32 v8, v172 offset:12672
	ds_write_b32 v8, v188 offset:12800
	ds_write_b32 v8, v173 offset:13200
	ds_write_b32 v8, v189 offset:13328
	ds_write_b32 v8, v174 offset:13728
	ds_write_b32 v8, v190 offset:13856
	ds_write_b32 v8, v175 offset:14256
	ds_write_b32 v8, v191 offset:14384
	s_waitcnt lgkmcnt(0)
	s_barrier
	s_cmp_eq_u32 s52, 0
	s_cbranch_scc1 .Lmy_sgu_last
	s_waitcnt vmcnt(24)
	ds_read_b128 v[212:215], v9
	ds_read_b128 v[216:219], v9 offset:16
	v_lshlrev_b32_e32 v244, 16, v228
	v_and_b32_e32 v245, 0xffff0000, v228
	v_lshlrev_b32_e32 v246, 16, v229
	v_and_b32_e32 v247, 0xffff0000, v229
	v_lshlrev_b32_e32 v248, 16, v230
	v_and_b32_e32 v249, 0xffff0000, v230
	v_lshlrev_b32_e32 v250, 16, v231
	v_and_b32_e32 v251, 0xffff0000, v231
	s_waitcnt lgkmcnt(0)
	v_mul_f32_e32 v244, v244, v212
	v_mul_f32_e32 v245, v245, v213
	v_mul_f32_e32 v246, v246, v214
	v_mul_f32_e32 v247, v247, v215
	v_mul_f32_e32 v248, v248, v216
	v_mul_f32_e32 v249, v249, v217
	v_mul_f32_e32 v250, v250, v218
	v_mul_f32_e32 v251, v251, v219
	v_cvt_pk_bf16_f32 v220, v244, v245
	v_cvt_pk_bf16_f32 v221, v246, v247
	v_cvt_pk_bf16_f32 v222, v248, v249
	v_cvt_pk_bf16_f32 v223, v250, v251
	global_store_dwordx4 v10, v[220:223], s[44:45]
	global_load_dwordx4 v[228:231], v10, s[20:21]
	ds_read_b128 v[212:215], v9 offset:16896
	ds_read_b128 v[216:219], v9 offset:16912
	v_lshlrev_b32_e32 v244, 16, v232
	v_and_b32_e32 v245, 0xffff0000, v232
	v_lshlrev_b32_e32 v246, 16, v233
	v_and_b32_e32 v247, 0xffff0000, v233
	v_lshlrev_b32_e32 v248, 16, v234
	v_and_b32_e32 v249, 0xffff0000, v234
	v_lshlrev_b32_e32 v250, 16, v235
	v_and_b32_e32 v251, 0xffff0000, v235
	s_waitcnt lgkmcnt(0)
	v_mul_f32_e32 v244, v244, v212
	v_mul_f32_e32 v245, v245, v213
	v_mul_f32_e32 v246, v246, v214
	v_mul_f32_e32 v247, v247, v215
	v_mul_f32_e32 v248, v248, v216
	v_mul_f32_e32 v249, v249, v217
	v_mul_f32_e32 v250, v250, v218
	v_mul_f32_e32 v251, v251, v219
	v_cvt_pk_bf16_f32 v220, v244, v245
	v_cvt_pk_bf16_f32 v221, v246, v247
	v_cvt_pk_bf16_f32 v222, v248, v249
	v_cvt_pk_bf16_f32 v223, v250, v251
	global_store_dwordx4 v11, v[220:223], s[44:45]
	global_load_dwordx4 v[232:235], v11, s[20:21]
	ds_read_b128 v[212:215], v9 offset:33792
	ds_read_b128 v[216:219], v9 offset:33808
	v_lshlrev_b32_e32 v244, 16, v236
	v_and_b32_e32 v245, 0xffff0000, v236
	v_lshlrev_b32_e32 v246, 16, v237
	v_and_b32_e32 v247, 0xffff0000, v237
	v_lshlrev_b32_e32 v248, 16, v238
	v_and_b32_e32 v249, 0xffff0000, v238
	v_lshlrev_b32_e32 v250, 16, v239
	v_and_b32_e32 v251, 0xffff0000, v239
	s_waitcnt lgkmcnt(0)
	v_mul_f32_e32 v244, v244, v212
	v_mul_f32_e32 v245, v245, v213
	v_mul_f32_e32 v246, v246, v214
	v_mul_f32_e32 v247, v247, v215
	v_mul_f32_e32 v248, v248, v216
	v_mul_f32_e32 v249, v249, v217
	v_mul_f32_e32 v250, v250, v218
	v_mul_f32_e32 v251, v251, v219
	v_cvt_pk_bf16_f32 v220, v244, v245
	v_cvt_pk_bf16_f32 v221, v246, v247
	v_cvt_pk_bf16_f32 v222, v248, v249
	v_cvt_pk_bf16_f32 v223, v250, v251
	global_store_dwordx4 v12, v[220:223], s[44:45]
	global_load_dwordx4 v[236:239], v12, s[20:21]
	ds_read_b128 v[212:215], v9 offset:50688
	ds_read_b128 v[216:219], v9 offset:50704
	v_lshlrev_b32_e32 v244, 16, v240
	v_and_b32_e32 v245, 0xffff0000, v240
	v_lshlrev_b32_e32 v246, 16, v241
	v_and_b32_e32 v247, 0xffff0000, v241
	v_lshlrev_b32_e32 v248, 16, v242
	v_and_b32_e32 v249, 0xffff0000, v242
	v_lshlrev_b32_e32 v250, 16, v243
	v_and_b32_e32 v251, 0xffff0000, v243
	s_waitcnt lgkmcnt(0)
	v_mul_f32_e32 v244, v244, v212
	v_mul_f32_e32 v245, v245, v213
	v_mul_f32_e32 v246, v246, v214
	v_mul_f32_e32 v247, v247, v215
	v_mul_f32_e32 v248, v248, v216
	v_mul_f32_e32 v249, v249, v217
	v_mul_f32_e32 v250, v250, v218
	v_mul_f32_e32 v251, v251, v219
	v_cvt_pk_bf16_f32 v220, v244, v245
	v_cvt_pk_bf16_f32 v221, v246, v247
	v_cvt_pk_bf16_f32 v222, v248, v249
	v_cvt_pk_bf16_f32 v223, v250, v251
	global_store_dwordx4 v13, v[220:223], s[44:45]
	global_load_dwordx4 v[240:243], v13, s[20:21]
	s_mov_b32 s44, s46
	s_mov_b32 s45, s47
	s_mov_b32 s101, s51
	s_barrier
	s_branch .Lmy_sgu_unit
.Lmy_sgu_last:
	s_waitcnt vmcnt(0)
	ds_read_b128 v[212:215], v9
	ds_read_b128 v[216:219], v9 offset:16
	v_lshlrev_b32_e32 v244, 16, v228
	v_and_b32_e32 v245, 0xffff0000, v228
	v_lshlrev_b32_e32 v246, 16, v229
	v_and_b32_e32 v247, 0xffff0000, v229
	v_lshlrev_b32_e32 v248, 16, v230
	v_and_b32_e32 v249, 0xffff0000, v230
	v_lshlrev_b32_e32 v250, 16, v231
	v_and_b32_e32 v251, 0xffff0000, v231
	s_waitcnt lgkmcnt(0)
	v_mul_f32_e32 v244, v244, v212
	v_mul_f32_e32 v245, v245, v213
	v_mul_f32_e32 v246, v246, v214
	v_mul_f32_e32 v247, v247, v215
	v_mul_f32_e32 v248, v248, v216
	v_mul_f32_e32 v249, v249, v217
	v_mul_f32_e32 v250, v250, v218
	v_mul_f32_e32 v251, v251, v219
	v_cvt_pk_bf16_f32 v220, v244, v245
	v_cvt_pk_bf16_f32 v221, v246, v247
	v_cvt_pk_bf16_f32 v222, v248, v249
	v_cvt_pk_bf16_f32 v223, v250, v251
	global_store_dwordx4 v10, v[220:223], s[44:45]
	ds_read_b128 v[212:215], v9 offset:16896
	ds_read_b128 v[216:219], v9 offset:16912
	v_lshlrev_b32_e32 v244, 16, v232
	v_and_b32_e32 v245, 0xffff0000, v232
	v_lshlrev_b32_e32 v246, 16, v233
	v_and_b32_e32 v247, 0xffff0000, v233
	v_lshlrev_b32_e32 v248, 16, v234
	v_and_b32_e32 v249, 0xffff0000, v234
	v_lshlrev_b32_e32 v250, 16, v235
	v_and_b32_e32 v251, 0xffff0000, v235
	s_waitcnt lgkmcnt(0)
	v_mul_f32_e32 v244, v244, v212
	v_mul_f32_e32 v245, v245, v213
	v_mul_f32_e32 v246, v246, v214
	v_mul_f32_e32 v247, v247, v215
	v_mul_f32_e32 v248, v248, v216
	v_mul_f32_e32 v249, v249, v217
	v_mul_f32_e32 v250, v250, v218
	v_mul_f32_e32 v251, v251, v219
	v_cvt_pk_bf16_f32 v220, v244, v245
	v_cvt_pk_bf16_f32 v221, v246, v247
	v_cvt_pk_bf16_f32 v222, v248, v249
	v_cvt_pk_bf16_f32 v223, v250, v251
	global_store_dwordx4 v11, v[220:223], s[44:45]
	ds_read_b128 v[212:215], v9 offset:33792
	ds_read_b128 v[216:219], v9 offset:33808
	v_lshlrev_b32_e32 v244, 16, v236
	v_and_b32_e32 v245, 0xffff0000, v236
	v_lshlrev_b32_e32 v246, 16, v237
	v_and_b32_e32 v247, 0xffff0000, v237
	v_lshlrev_b32_e32 v248, 16, v238
	v_and_b32_e32 v249, 0xffff0000, v238
	v_lshlrev_b32_e32 v250, 16, v239
	v_and_b32_e32 v251, 0xffff0000, v239
	s_waitcnt lgkmcnt(0)
	v_mul_f32_e32 v244, v244, v212
	v_mul_f32_e32 v245, v245, v213
	v_mul_f32_e32 v246, v246, v214
	v_mul_f32_e32 v247, v247, v215
	v_mul_f32_e32 v248, v248, v216
	v_mul_f32_e32 v249, v249, v217
	v_mul_f32_e32 v250, v250, v218
	v_mul_f32_e32 v251, v251, v219
	v_cvt_pk_bf16_f32 v220, v244, v245
	v_cvt_pk_bf16_f32 v221, v246, v247
	v_cvt_pk_bf16_f32 v222, v248, v249
	v_cvt_pk_bf16_f32 v223, v250, v251
	global_store_dwordx4 v12, v[220:223], s[44:45]
	ds_read_b128 v[212:215], v9 offset:50688
	ds_read_b128 v[216:219], v9 offset:50704
	v_lshlrev_b32_e32 v244, 16, v240
	v_and_b32_e32 v245, 0xffff0000, v240
	v_lshlrev_b32_e32 v246, 16, v241
	v_and_b32_e32 v247, 0xffff0000, v241
	v_lshlrev_b32_e32 v248, 16, v242
	v_and_b32_e32 v249, 0xffff0000, v242
	v_lshlrev_b32_e32 v250, 16, v243
	v_and_b32_e32 v251, 0xffff0000, v243
	s_waitcnt lgkmcnt(0)
	v_mul_f32_e32 v244, v244, v212
	v_mul_f32_e32 v245, v245, v213
	v_mul_f32_e32 v246, v246, v214
	v_mul_f32_e32 v247, v247, v215
	v_mul_f32_e32 v248, v248, v216
	v_mul_f32_e32 v249, v249, v217
	v_mul_f32_e32 v250, v250, v218
	v_mul_f32_e32 v251, v251, v219
	v_cvt_pk_bf16_f32 v220, v244, v245
	v_cvt_pk_bf16_f32 v221, v246, v247
	v_cvt_pk_bf16_f32 v222, v248, v249
	v_cvt_pk_bf16_f32 v223, v250, v251
	global_store_dwordx4 v13, v[220:223], s[44:45]
	s_mov_b32 s101, s51
	s_barrier
